# same as previous plus a full LDS drain (lgkmcnt 0) before the per-tile barrier in the mixer-A loop (strict WAR safety on the K/V double buffer)
# baseline (speedup 1.0000x reference)
.Lmya_nopf_e:
	v_exp_f32_e32 v89, v89
	v_add_f32_e32 v191, v87, v191
	v_exp_f32_e32 v90, v90
	v_cvt_pk_bf16_f32 v146, v86, v87
	v_add_f32_e32 v190, v88, v190
	v_exp_f32_e32 v91, v91
	v_add_f32_e32 v191, v89, v191
	s_waitcnt lgkmcnt(8)
	v_mfma_f32_32x32x16_bf16 v[34:49], v[176:179], v[140:143], v[34:49]
	v_exp_f32_e32 v92, v92
	v_cvt_pk_bf16_f32 v147, v88, v89
	v_add_f32_e32 v190, v90, v190
	v_exp_f32_e32 v93, v93
	v_add_f32_e32 v191, v91, v191
	v_exp_f32_e32 v94, v94
	v_cvt_pk_bf16_f32 v148, v90, v91
	s_waitcnt lgkmcnt(5)
	v_mfma_f32_32x32x16_bf16 v[18:33], v[180:183], v[136:139], v[18:33]
	v_add_f32_e32 v190, v92, v190
	v_exp_f32_e32 v95, v95
	v_add_f32_e32 v191, v93, v191
	v_exp_f32_e32 v96, v96
	v_cvt_pk_bf16_f32 v149, v92, v93
	v_add_f32_e32 v190, v94, v190
	s_waitcnt lgkmcnt(2)
	v_mfma_f32_32x32x16_bf16 v[18:33], v[184:187], v[140:143], v[18:33]
	v_exp_f32_e32 v97, v97
	v_add_f32_e32 v191, v95, v191
	v_cvt_pk_bf16_f32 v150, v94, v95
	v_add_f32_e32 v190, v96, v190
	v_add_f32_e32 v191, v97, v191
	v_cvt_pk_bf16_f32 v151, v96, v97
	s_waitcnt lgkmcnt(0)
	v_mfma_f32_32x32x16_bf16 v[82:97], v[152:155], v[102:105], 0
	v_exp_f32_e32 v66, v66
	v_exp_f32_e32 v67, v67
	v_exp_f32_e32 v68, v68
	v_add_f32_e32 v188, v66, v188
	v_exp_f32_e32 v69, v69
	v_add_f32_e32 v189, v67, v189
	v_exp_f32_e32 v70, v70
	v_mfma_f32_32x32x16_bf16 v[82:97], v[156:159], v[98:101], v[82:97]
	v_cvt_pk_bf16_f32 v136, v66, v67
	v_add_f32_e32 v188, v68, v188
	v_exp_f32_e32 v71, v71
	v_add_f32_e32 v189, v69, v189
	v_exp_f32_e32 v72, v72
	v_cvt_pk_bf16_f32 v137, v68, v69
	v_add_f32_e32 v188, v70, v188
	v_mfma_f32_32x32x16_bf16 v[50:65], v[172:175], v[144:147], v[50:65]
	ds_read_b64_tr_b16 v[172:173], v194 offset:13824
	ds_read_b64_tr_b16 v[174:175], v194 offset:14976
	v_exp_f32_e32 v73, v73
	v_add_f32_e32 v189, v71, v189
	v_exp_f32_e32 v74, v74
	v_cvt_pk_bf16_f32 v138, v70, v71
	v_add_f32_e32 v188, v72, v188
	v_exp_f32_e32 v75, v75
	v_add_f32_e32 v189, v73, v189
	v_mfma_f32_32x32x16_bf16 v[50:65], v[176:179], v[148:151], v[50:65]
	ds_read_b64_tr_b16 v[176:177], v194 offset:16128
	ds_read_b64_tr_b16 v[178:179], v194 offset:17280
	v_exp_f32_e32 v76, v76
	v_cvt_pk_bf16_f32 v139, v72, v73
	v_add_f32_e32 v188, v74, v188
	v_exp_f32_e32 v77, v77
	v_add_f32_e32 v189, v75, v189
	v_exp_f32_e32 v78, v78
	v_cvt_pk_bf16_f32 v140, v74, v75
	v_mfma_f32_32x32x16_bf16 v[2:17], v[180:183], v[144:147], v[2:17]
	ds_read_b64_tr_b16 v[180:181], v194 offset:13888
	ds_read_b64_tr_b16 v[182:183], v194 offset:15040
	v_add_f32_e32 v188, v76, v188
	v_exp_f32_e32 v79, v79
	v_add_f32_e32 v189, v77, v189
	v_exp_f32_e32 v80, v80
	v_cvt_pk_bf16_f32 v141, v76, v77
	v_add_f32_e32 v188, v78, v188
	v_mfma_f32_32x32x16_bf16 v[2:17], v[184:187], v[148:151], v[2:17]
	ds_read_b64_tr_b16 v[184:185], v194 offset:16192
	ds_read_b64_tr_b16 v[186:187], v194 offset:17344
	v_exp_f32_e32 v81, v81
	v_add_f32_e32 v189, v79, v189
	v_cvt_pk_bf16_f32 v142, v78, v79
	v_add_f32_e32 v188, v80, v188
	v_add_f32_e32 v189, v81, v189
	v_cvt_pk_bf16_f32 v143, v80, v81
	s_waitcnt lgkmcnt(0)
	s_barrier
	ds_read_b128 v[152:155], v193 offset:18432
	ds_read_b128 v[156:159], v193 offset:18464
	v_mfma_f32_32x32x16_bf16 v[34:49], v[172:175], v[136:139], v[34:49]
	v_exp_f32_e32 v82, v82
	v_exp_f32_e32 v83, v83
	v_exp_f32_e32 v84, v84
	v_add_f32_e32 v190, v82, v190
	v_exp_f32_e32 v85, v85
	v_add_f32_e32 v191, v83, v191
	v_exp_f32_e32 v86, v86
	v_mfma_f32_32x32x16_bf16 v[34:49], v[176:179], v[140:143], v[34:49]
	v_cvt_pk_bf16_f32 v144, v82, v83
	v_add_f32_e32 v190, v84, v190
	v_exp_f32_e32 v87, v87
	v_add_f32_e32 v191, v85, v191
	v_exp_f32_e32 v88, v88
	v_cvt_pk_bf16_f32 v145, v84, v85
	v_add_f32_e32 v190, v86, v190
	v_mfma_f32_32x32x16_bf16 v[18:33], v[180:183], v[136:139], v[18:33]
	v_exp_f32_e32 v89, v89
	v_add_f32_e32 v191, v87, v191
	v_exp_f32_e32 v90, v90
	v_cvt_pk_bf16_f32 v146, v86, v87
	v_add_f32_e32 v190, v88, v190
	v_exp_f32_e32 v91, v91
	v_add_f32_e32 v191, v89, v191
	s_waitcnt lgkmcnt(0)
	v_mfma_f32_32x32x16_bf16 v[66:81], v[152:155], v[110:113], 0
	v_exp_f32_e32 v92, v92
	v_cvt_pk_bf16_f32 v147, v88, v89
	v_add_f32_e32 v190, v90, v190
	v_exp_f32_e32 v93, v93
	v_add_f32_e32 v191, v91, v191
	v_exp_f32_e32 v94, v94
	v_cvt_pk_bf16_f32 v148, v90, v91
	v_mfma_f32_32x32x16_bf16 v[66:81], v[156:159], v[106:109], v[66:81]
	ds_read_b128 v[152:155], v193 offset:18496
	ds_read_b128 v[156:159], v193 offset:18528
	v_add_f32_e32 v190, v92, v190
	v_exp_f32_e32 v95, v95
	v_add_f32_e32 v191, v93, v191
	v_exp_f32_e32 v96, v96
	v_cvt_pk_bf16_f32 v149, v92, v93
	v_add_f32_e32 v190, v94, v190
	v_mfma_f32_32x32x16_bf16 v[18:33], v[184:187], v[140:143], v[18:33]
	v_exp_f32_e32 v97, v97
	v_add_f32_e32 v191, v95, v191
	v_cvt_pk_bf16_f32 v150, v94, v95
	v_add_f32_e32 v190, v96, v190
	v_add_f32_e32 v191, v97, v191
	v_cvt_pk_bf16_f32 v151, v96, v97
	s_waitcnt lgkmcnt(0)
	v_mfma_f32_32x32x16_bf16 v[82:97], v[152:155], v[102:105], 0
	v_exp_f32_e32 v66, v66
	v_exp_f32_e32 v67, v67
	v_exp_f32_e32 v68, v68
	v_add_f32_e32 v188, v66, v188
	v_exp_f32_e32 v69, v69
	v_add_f32_e32 v189, v67, v189
	v_exp_f32_e32 v70, v70
	v_mfma_f32_32x32x16_bf16 v[82:97], v[156:159], v[98:101], v[82:97]
	ds_read_b128 v[152:155], v193 offset:23040
	ds_read_b128 v[156:159], v193 offset:23072
	s_waitcnt vmcnt(0)
	ds_write_b128 v132, v[114:117] offset:0
	v_cvt_pk_bf16_f32 v136, v66, v67
	v_add_f32_e32 v188, v68, v188
	v_exp_f32_e32 v71, v71
	v_add_f32_e32 v189, v69, v189
	v_exp_f32_e32 v72, v72
	v_cvt_pk_bf16_f32 v137, v68, v69
	v_add_f32_e32 v188, v70, v188
	v_mfma_f32_32x32x16_bf16 v[50:65], v[172:175], v[144:147], v[50:65]
	ds_read_b64_tr_b16 v[172:173], v194 offset:27648
	ds_read_b64_tr_b16 v[174:175], v194 offset:28800
	ds_write_b128 v132, v[118:121] offset:9216
	v_exp_f32_e32 v73, v73
	v_add_f32_e32 v189, v71, v189
	v_exp_f32_e32 v74, v74
	v_cvt_pk_bf16_f32 v138, v70, v71
	v_add_f32_e32 v188, v72, v188
	v_exp_f32_e32 v75, v75
	v_add_f32_e32 v189, v73, v189
	v_mfma_f32_32x32x16_bf16 v[50:65], v[176:179], v[148:151], v[50:65]
	ds_read_b64_tr_b16 v[176:177], v194 offset:29952
	ds_read_b64_tr_b16 v[178:179], v194 offset:31104
	ds_write_b128 v132, v[122:125] offset:4608
	v_exp_f32_e32 v76, v76
	v_cvt_pk_bf16_f32 v139, v72, v73
	v_add_f32_e32 v188, v74, v188
	v_exp_f32_e32 v77, v77
	v_add_f32_e32 v189, v75, v189
	v_exp_f32_e32 v78, v78
	v_cvt_pk_bf16_f32 v140, v74, v75
	v_mfma_f32_32x32x16_bf16 v[2:17], v[180:183], v[144:147], v[2:17]
	ds_read_b64_tr_b16 v[180:181], v194 offset:27712
	ds_read_b64_tr_b16 v[182:183], v194 offset:28864
	ds_write_b128 v132, v[126:129] offset:13824
	v_add_f32_e32 v188, v76, v188
	v_exp_f32_e32 v79, v79
	v_add_f32_e32 v189, v77, v189
	v_exp_f32_e32 v80, v80
	v_cvt_pk_bf16_f32 v141, v76, v77
	v_add_f32_e32 v188, v78, v188
	v_mfma_f32_32x32x16_bf16 v[2:17], v[184:187], v[148:151], v[2:17]
	ds_read_b64_tr_b16 v[184:185], v194 offset:30016
	ds_read_b64_tr_b16 v[186:187], v194 offset:31168
	v_exp_f32_e32 v81, v81
	v_add_f32_e32 v189, v79, v189
	v_cvt_pk_bf16_f32 v142, v78, v79
	v_add_f32_e32 v188, v80, v188
	v_add_f32_e32 v189, v81, v189
	v_cvt_pk_bf16_f32 v143, v80, v81
	s_waitcnt lgkmcnt(12)
	v_mfma_f32_32x32x16_bf16 v[66:81], v[152:155], v[110:113], 0
	v_exp_f32_e32 v82, v82
	v_exp_f32_e32 v83, v83
	v_exp_f32_e32 v84, v84
	v_add_f32_e32 v190, v82, v190
	v_exp_f32_e32 v85, v85
	v_add_f32_e32 v191, v83, v191
	v_exp_f32_e32 v86, v86
	v_mfma_f32_32x32x16_bf16 v[66:81], v[156:159], v[106:109], v[66:81]
	ds_read_b128 v[152:155], v193 offset:23104
	ds_read_b128 v[156:159], v193 offset:23136
	v_cvt_pk_bf16_f32 v144, v82, v83
	v_add_f32_e32 v190, v84, v190
	v_exp_f32_e32 v87, v87
	v_add_f32_e32 v191, v85, v191
	v_exp_f32_e32 v88, v88
	v_cvt_pk_bf16_f32 v145, v84, v85
	v_add_f32_e32 v190, v86, v190
	s_waitcnt lgkmcnt(11)
	v_mfma_f32_32x32x16_bf16 v[34:49], v[172:175], v[136:139], v[34:49]
	s_cmp_lt_u32 s6, 62
	s_cbranch_scc0 .Lmya_nopf_o
	v_lshl_add_u64 v[164:165], v[160:161], 0, s[70:71]
	global_load_dwordx4 v[114:117], v[160:161], off offset:512
	global_load_dwordx4 v[118:121], v[160:161], off offset:1024
	global_load_dwordx4 v[122:125], v[164:165], off offset:512
	global_load_dwordx4 v[126:129], v[164:165], off offset:1024
	v_lshl_add_u64 v[160:161], v[160:161], 0, s[36:37]
.Lmya_nopf_o:
	v_exp_f32_e32 v89, v89
	v_add_f32_e32 v191, v87, v191
	v_exp_f32_e32 v90, v90
	v_cvt_pk_bf16_f32 v146, v86, v87
	v_add_f32_e32 v190, v88, v190
	v_exp_f32_e32 v91, v91
	v_add_f32_e32 v191, v89, v191
	s_waitcnt lgkmcnt(8)
	v_mfma_f32_32x32x16_bf16 v[34:49], v[176:179], v[140:143], v[34:49]
	v_exp_f32_e32 v92, v92
	v_cvt_pk_bf16_f32 v147, v88, v89
	v_add_f32_e32 v190, v90, v190
	v_exp_f32_e32 v93, v93
	v_add_f32_e32 v191, v91, v191
	v_exp_f32_e32 v94, v94
	v_cvt_pk_bf16_f32 v148, v90, v91
	s_waitcnt lgkmcnt(5)
	v_mfma_f32_32x32x16_bf16 v[18:33], v[180:183], v[136:139], v[18:33]
	v_add_f32_e32 v190, v92, v190
	v_exp_f32_e32 v95, v95
	v_add_f32_e32 v191, v93, v191
	v_exp_f32_e32 v96, v96
	v_cvt_pk_bf16_f32 v149, v92, v93
	v_add_f32_e32 v190, v94, v190
	s_waitcnt lgkmcnt(2)
	v_mfma_f32_32x32x16_bf16 v[18:33], v[184:187], v[140:143], v[18:33]
	v_exp_f32_e32 v97, v97
	v_add_f32_e32 v191, v95, v191
	v_cvt_pk_bf16_f32 v150, v94, v95
	v_add_f32_e32 v190, v96, v190
	v_add_f32_e32 v191, v97, v191
	v_cvt_pk_bf16_f32 v151, v96, v97
	s_waitcnt lgkmcnt(0)
	v_mfma_f32_32x32x16_bf16 v[82:97], v[152:155], v[102:105], 0
	v_exp_f32_e32 v66, v66
	v_exp_f32_e32 v67, v67
	v_exp_f32_e32 v68, v68
	v_add_f32_e32 v188, v66, v188
	v_exp_f32_e32 v69, v69
	v_add_f32_e32 v189, v67, v189
	v_exp_f32_e32 v70, v70
	v_mfma_f32_32x32x16_bf16 v[82:97], v[156:159], v[98:101], v[82:97]
	v_cvt_pk_bf16_f32 v136, v66, v67
	v_add_f32_e32 v188, v68, v188
	v_exp_f32_e32 v71, v71
	v_add_f32_e32 v189, v69, v189
	v_exp_f32_e32 v72, v72
	v_cvt_pk_bf16_f32 v137, v68, v69
	v_add_f32_e32 v188, v70, v188
	v_mfma_f32_32x32x16_bf16 v[50:65], v[172:175], v[144:147], v[50:65]
	ds_read_b64_tr_b16 v[172:173], v194 offset:32256
	ds_read_b64_tr_b16 v[174:175], v194 offset:33408
	v_exp_f32_e32 v73, v73
	v_add_f32_e32 v189, v71, v189
	v_exp_f32_e32 v74, v74
	v_cvt_pk_bf16_f32 v138, v70, v71
	v_add_f32_e32 v188, v72, v188
	v_exp_f32_e32 v75, v75
	v_add_f32_e32 v189, v73, v189
	v_mfma_f32_32x32x16_bf16 v[50:65], v[176:179], v[148:151], v[50:65]
	ds_read_b64_tr_b16 v[176:177], v194 offset:34560
	ds_read_b64_tr_b16 v[178:179], v194 offset:35712
	v_exp_f32_e32 v76, v76
	v_cvt_pk_bf16_f32 v139, v72, v73
	v_add_f32_e32 v188, v74, v188
	v_exp_f32_e32 v77, v77
	v_add_f32_e32 v189, v75, v189
	v_exp_f32_e32 v78, v78
	v_cvt_pk_bf16_f32 v140, v74, v75
	v_mfma_f32_32x32x16_bf16 v[2:17], v[180:183], v[144:147], v[2:17]
	ds_read_b64_tr_b16 v[180:181], v194 offset:32320
	ds_read_b64_tr_b16 v[182:183], v194 offset:33472
	v_add_f32_e32 v188, v76, v188
	v_exp_f32_e32 v79, v79
	v_add_f32_e32 v189, v77, v189
	v_exp_f32_e32 v80, v80
	v_cvt_pk_bf16_f32 v141, v76, v77
	v_add_f32_e32 v188, v78, v188
	v_mfma_f32_32x32x16_bf16 v[2:17], v[184:187], v[148:151], v[2:17]
	ds_read_b64_tr_b16 v[184:185], v194 offset:34624
	ds_read_b64_tr_b16 v[186:187], v194 offset:35776
	v_exp_f32_e32 v81, v81
	v_add_f32_e32 v189, v79, v189
	v_cvt_pk_bf16_f32 v142, v78, v79
	v_add_f32_e32 v188, v80, v188
	v_add_f32_e32 v189, v81, v189
	v_cvt_pk_bf16_f32 v143, v80, v81
	s_waitcnt lgkmcnt(0)
	s_barrier
	ds_read_b128 v[152:155], v193 offset:0
	ds_read_b128 v[156:159], v193 offset:32
	v_mfma_f32_32x32x16_bf16 v[34:49], v[172:175], v[136:139], v[34:49]
	v_exp_f32_e32 v82, v82
	v_exp_f32_e32 v83, v83
	v_exp_f32_e32 v84, v84
	v_add_f32_e32 v190, v82, v190
	v_exp_f32_e32 v85, v85
	v_add_f32_e32 v191, v83, v191
	v_exp_f32_e32 v86, v86
	v_mfma_f32_32x32x16_bf16 v[34:49], v[176:179], v[140:143], v[34:49]
	v_cvt_pk_bf16_f32 v144, v82, v83
	v_add_f32_e32 v190, v84, v190
	v_exp_f32_e32 v87, v87
	v_add_f32_e32 v191, v85, v191
	v_exp_f32_e32 v88, v88
	v_cvt_pk_bf16_f32 v145, v84, v85
	v_add_f32_e32 v190, v86, v190
	v_mfma_f32_32x32x16_bf16 v[18:33], v[180:183], v[136:139], v[18:33]
	v_exp_f32_e32 v89, v89
	v_add_f32_e32 v191, v87, v191
	v_exp_f32_e32 v90, v90
	v_cvt_pk_bf16_f32 v146, v86, v87
	v_add_f32_e32 v190, v88, v190
	v_exp_f32_e32 v91, v91
	v_add_f32_e32 v191, v89, v191
	s_waitcnt lgkmcnt(0)
	v_mfma_f32_32x32x16_bf16 v[66:81], v[152:155], v[110:113], 0
	v_exp_f32_e32 v92, v92
	v_cvt_pk_bf16_f32 v147, v88, v89
	v_add_f32_e32 v190, v90, v190
	v_exp_f32_e32 v93, v93
	v_add_f32_e32 v191, v91, v191
	v_exp_f32_e32 v94, v94
	v_cvt_pk_bf16_f32 v148, v90, v91
	v_mfma_f32_32x32x16_bf16 v[66:81], v[156:159], v[106:109], v[66:81]
	ds_read_b128 v[152:155], v193 offset:64
	ds_read_b128 v[156:159], v193 offset:96
	v_add_f32_e32 v190, v92, v190
	v_exp_f32_e32 v95, v95
	v_add_f32_e32 v191, v93, v191
	v_exp_f32_e32 v96, v96
	v_cvt_pk_bf16_f32 v149, v92, v93
	v_add_f32_e32 v190, v94, v190
	v_mfma_f32_32x32x16_bf16 v[18:33], v[184:187], v[140:143], v[18:33]
	v_exp_f32_e32 v97, v97
	v_add_f32_e32 v191, v95, v191
	v_cvt_pk_bf16_f32 v150, v94, v95
	v_add_f32_e32 v190, v96, v190
	v_add_f32_e32 v191, v97, v191
	v_cvt_pk_bf16_f32 v151, v96, v97
	s_add_u32 s6, s6, 2
	s_cmp_lt_u32 s6, 64
	s_cbranch_scc1 .Lmya_loop
	v_mfma_f32_32x32x16_bf16 v[50:65], v[172:175], v[144:147], v[50:65]
	v_mfma_f32_32x32x16_bf16 v[50:65], v[176:179], v[148:151], v[50:65]
	v_mfma_f32_32x32x16_bf16 v[2:17], v[180:183], v[144:147], v[2:17]
	v_mfma_f32_32x32x16_bf16 v[2:17], v[184:187], v[148:151], v[2:17]
	v_add_f32_e32 v0, v188, v189
	v_add_f32_e32 v78, v190, v191
	s_add_u32 s6, s0, s34
	s_addc_u32 s7, s1, s35
	s_waitcnt lgkmcnt(0)
	s_barrier
	global_load_dword v66, v1, s[6:7]
	v_and_b32_e32 v68, 64, v211
	v_xor_b32_e32 v67, 32, v211
	v_add_u32_e32 v68, 64, v68
	v_cmp_lt_i32_e32 vcc, v67, v68
	s_nop 1
	v_cndmask_b32_e32 v67, v211, v67, vcc
	v_lshlrev_b32_e32 v67, 2, v67
	ds_bpermute_b32 v68, v67, v0
	ds_bpermute_b32 v69, v67, v78
	s_waitcnt lgkmcnt(1)
	v_add_f32_e32 v0, v0, v68
	v_div_scale_f32 v68, s[6:7], v0, v0, 1.0
	v_rcp_f32_e32 v70, v68
	v_div_scale_f32 v71, vcc, 1.0, v0, 1.0
	s_waitcnt lgkmcnt(0)
	v_add_f32_e32 v69, v78, v69
	v_fma_f32 v72, -v68, v70, 1.0
	v_fmac_f32_e32 v70, v72, v70
	v_mul_f32_e32 v72, v71, v70
	v_fma_f32 v73, -v68, v72, v71
	v_fmac_f32_e32 v72, v73, v70
	v_fma_f32 v68, -v68, v72, v71
	v_div_fmas_f32 v68, v68, v70, v72
	v_div_fixup_f32 v0, v68, v0, 1.0
	s_waitcnt vmcnt(0)
	v_div_scale_f32 v70, s[6:7], v69, v69, v66
	v_rcp_f32_e32 v71, v70
	v_div_scale_f32 v68, vcc, v66, v69, v66
	s_mov_b64 s[6:7], 0
	v_fma_f32 v72, -v70, v71, 1.0
	v_fmac_f32_e32 v71, v72, v71
	v_mul_f32_e32 v72, v68, v71
	v_fma_f32 v73, -v70, v72, v68
	v_fmac_f32_e32 v72, v73, v71
	v_fma_f32 v68, -v70, v72, v68
	v_div_fmas_f32 v68, v68, v71, v72
	v_div_fixup_f32 v66, v68, v69, v66
	v_pk_mul_f32 v[50:51], v[50:51], v[66:67] op_sel_hi:[1,0]
	v_pk_mul_f32 v[52:53], v[52:53], v[66:67] op_sel_hi:[1,0]
	v_pk_mul_f32 v[70:71], v[58:59], v[66:67] op_sel_hi:[1,0]
	v_pk_mul_f32 v[2:3], v[2:3], v[66:67] op_sel_hi:[1,0]
	v_pk_mul_f32 v[8:9], v[8:9], v[66:67] op_sel_hi:[1,0]
	v_pk_mul_f32 v[10:11], v[10:11], v[66:67] op_sel_hi:[1,0]
	v_pk_fma_f32 v[58:59], v[34:35], v[0:1], v[50:51] op_sel_hi:[1,0,1] neg_lo:[0,0,1] neg_hi:[0,0,1]
	v_pk_mul_f32 v[54:55], v[54:55], v[66:67] op_sel_hi:[1,0]
	v_pk_mul_f32 v[68:69], v[56:57], v[66:67] op_sel_hi:[1,0]
	v_pk_mul_f32 v[60:61], v[60:61], v[66:67] op_sel_hi:[1,0]
	v_pk_mul_f32 v[62:63], v[62:63], v[66:67] op_sel_hi:[1,0]
	v_pk_mul_f32 v[64:65], v[64:65], v[66:67] op_sel_hi:[1,0]
	v_pk_mul_f32 v[4:5], v[4:5], v[66:67] op_sel_hi:[1,0]
	v_pk_mul_f32 v[6:7], v[6:7], v[66:67] op_sel_hi:[1,0]
	v_pk_mul_f32 v[12:13], v[12:13], v[66:67] op_sel_hi:[1,0]
	v_pk_mul_f32 v[14:15], v[14:15], v[66:67] op_sel_hi:[1,0]
	v_pk_mul_f32 v[16:17], v[16:17], v[66:67] op_sel_hi:[1,0]
	v_pk_fma_f32 v[56:57], v[36:37], v[0:1], v[52:53] op_sel_hi:[1,0,1] neg_lo:[0,0,1] neg_hi:[0,0,1]
	v_pk_fma_f32 v[36:37], v[18:19], v[0:1], v[2:3] op_sel_hi:[1,0,1] neg_lo:[0,0,1] neg_hi:[0,0,1]
	v_pk_fma_f32 v[18:19], v[24:25], v[0:1], v[8:9] op_sel_hi:[1,0,1] neg_lo:[0,0,1] neg_hi:[0,0,1]
	v_pk_fma_f32 v[8:9], v[26:27], v[0:1], v[10:11] op_sel_hi:[1,0,1] neg_lo:[0,0,1] neg_hi:[0,0,1]
	v_pk_mul_f32 v[10:11], v[58:59], v[58:59]
	v_pk_fma_f32 v[54:55], v[38:39], v[0:1], v[54:55] op_sel_hi:[1,0,1] neg_lo:[0,0,1] neg_hi:[0,0,1]
	v_pk_fma_f32 v[52:53], v[40:41], v[0:1], v[68:69] op_sel_hi:[1,0,1] neg_lo:[0,0,1] neg_hi:[0,0,1]
	v_pk_fma_f32 v[50:51], v[42:43], v[0:1], v[70:71] op_sel_hi:[1,0,1] neg_lo:[0,0,1] neg_hi:[0,0,1]
	v_pk_fma_f32 v[42:43], v[44:45], v[0:1], v[60:61] op_sel_hi:[1,0,1] neg_lo:[0,0,1] neg_hi:[0,0,1]
	v_pk_fma_f32 v[40:41], v[46:47], v[0:1], v[62:63] op_sel_hi:[1,0,1] neg_lo:[0,0,1] neg_hi:[0,0,1]
	v_pk_fma_f32 v[38:39], v[48:49], v[0:1], v[64:65] op_sel_hi:[1,0,1] neg_lo:[0,0,1] neg_hi:[0,0,1]
	v_pk_fma_f32 v[34:35], v[20:21], v[0:1], v[4:5] op_sel_hi:[1,0,1] neg_lo:[0,0,1] neg_hi:[0,0,1]
	v_pk_fma_f32 v[20:21], v[22:23], v[0:1], v[6:7] op_sel_hi:[1,0,1] neg_lo:[0,0,1] neg_hi:[0,0,1]
	v_pk_fma_f32 v[6:7], v[28:29], v[0:1], v[12:13] op_sel_hi:[1,0,1] neg_lo:[0,0,1] neg_hi:[0,0,1]
	v_pk_fma_f32 v[4:5], v[30:31], v[0:1], v[14:15] op_sel_hi:[1,0,1] neg_lo:[0,0,1] neg_hi:[0,0,1]
	v_pk_fma_f32 v[2:3], v[32:33], v[0:1], v[16:17] op_sel_hi:[1,0,1] neg_lo:[0,0,1] neg_hi:[0,0,1]
	v_pk_mul_f32 v[12:13], v[56:57], v[56:57]
	v_add_f32_e32 v0, v10, v11
	v_add_f32_e32 v0, v12, v0
	v_pk_mul_f32 v[14:15], v[54:55], v[54:55]
	v_add_f32_e32 v0, v13, v0
	v_add_f32_e32 v0, v14, v0
	v_pk_mul_f32 v[16:17], v[52:53], v[52:53]
	v_add_f32_e32 v0, v15, v0
	v_add_f32_e32 v0, v16, v0
	v_pk_mul_f32 v[22:23], v[50:51], v[50:51]
	v_add_f32_e32 v0, v17, v0
	v_add_f32_e32 v0, v22, v0
	v_pk_mul_f32 v[24:25], v[42:43], v[42:43]
	v_add_f32_e32 v0, v23, v0
	v_add_f32_e32 v0, v24, v0
	v_pk_mul_f32 v[26:27], v[40:41], v[40:41]
	v_add_f32_e32 v0, v25, v0
	v_add_f32_e32 v0, v26, v0
	v_pk_mul_f32 v[28:29], v[38:39], v[38:39]
	v_add_f32_e32 v0, v27, v0
	v_add_f32_e32 v0, v28, v0
	v_pk_mul_f32 v[30:31], v[36:37], v[36:37]
	v_add_f32_e32 v0, v29, v0
	v_add_f32_e32 v0, v30, v0
	v_pk_mul_f32 v[32:33], v[34:35], v[34:35]
	v_add_f32_e32 v0, v31, v0
	v_add_f32_e32 v0, v32, v0
	v_pk_mul_f32 v[44:45], v[20:21], v[20:21]
	v_add_f32_e32 v0, v33, v0
	v_add_f32_e32 v0, v44, v0
	v_pk_mul_f32 v[46:47], v[18:19], v[18:19]
	v_add_f32_e32 v0, v45, v0
	v_add_f32_e32 v0, v46, v0
	v_pk_mul_f32 v[48:49], v[8:9], v[8:9]
	v_add_f32_e32 v0, v47, v0
	v_add_f32_e32 v0, v48, v0
	v_pk_mul_f32 v[60:61], v[6:7], v[6:7]
	v_add_f32_e32 v0, v49, v0
	v_add_f32_e32 v0, v60, v0
	v_pk_mul_f32 v[62:63], v[4:5], v[4:5]
	v_add_f32_e32 v0, v61, v0
	v_add_f32_e32 v0, v62, v0
	v_pk_mul_f32 v[64:65], v[2:3], v[2:3]
	v_add_f32_e32 v0, v63, v0
	v_add_f32_e32 v0, v64, v0
	v_add_f32_e32 v0, v65, v0
	ds_bpermute_b32 v10, v67, v0
